# norm phases: gain/scale/shift loads of both rows hoisted and issued at once (were 8 serialized L2 round trips per iteration)
# speedup vs baseline: 1.0298x; 1.0161x over previous
.LBB0_442:
	s_or_b64 exec, exec, s[4:5]
	s_waitcnt vmcnt(0)
	v_mov_b32_e32 v53, v185
	v_min_i32_e32 v98, 0x8000, v32
	v_ashrrev_i32_e32 v98, 11, v98
	v_mul_hi_i32_i24_e32 v97, 0x6000, v98
	v_mul_i32_i24_e32 v96, 0x6000, v98
	v_lshl_add_u64 v[96:97], s[8:9], 0, v[96:97]
	s_mov_b64 s[4:5], 0x1000
	v_lshl_add_u64 v[94:95], v[96:97], 0, s[4:5]
	v_lshl_add_u64 v[94:95], v[94:95], 0, v[52:53]
	v_lshl_add_u64 v[96:97], v[96:97], 0, v[52:53]
	global_load_dwordx4 v[100:103], v[42:43], off
	global_load_dwordx4 v[104:107], v[42:43], off offset:1024
	global_load_dwordx4 v[108:111], v[42:43], off offset:2048
	global_load_dwordx4 v[112:115], v[42:43], off offset:3072
	global_load_dwordx4 v[116:119], v[94:95], off
	global_load_dwordx4 v[120:123], v[94:95], off offset:1024
	global_load_dwordx4 v[124:127], v[94:95], off offset:2048
	global_load_dwordx4 v[128:131], v[94:95], off offset:3072
	global_load_dwordx4 v[132:135], v[96:97], off
	global_load_dwordx4 v[136:139], v[96:97], off offset:1024
	global_load_dwordx4 v[140:143], v[96:97], off offset:2048
	global_load_dwordx4 v[144:147], v[96:97], off offset:3072
	v_min_i32_e32 v98, 0x8000, v62
	v_ashrrev_i32_e32 v98, 11, v98
	v_mul_hi_i32_i24_e32 v97, 0x6000, v98
	v_mul_i32_i24_e32 v96, 0x6000, v98
	v_lshl_add_u64 v[96:97], s[8:9], 0, v[96:97]
	s_mov_b64 s[4:5], 0x1000
	v_lshl_add_u64 v[94:95], v[96:97], 0, s[4:5]
	v_lshl_add_u64 v[94:95], v[94:95], 0, v[52:53]
	v_lshl_add_u64 v[96:97], v[96:97], 0, v[52:53]
	global_load_dwordx4 v[148:151], v[94:95], off
	global_load_dwordx4 v[152:155], v[94:95], off offset:1024
	global_load_dwordx4 v[156:159], v[94:95], off offset:2048
	global_load_dwordx4 v[160:163], v[94:95], off offset:3072
	global_load_dwordx4 v[164:167], v[96:97], off
	global_load_dwordx4 v[168:171], v[96:97], off offset:1024
	global_load_dwordx4 v[172:175], v[96:97], off offset:2048
	global_load_dwordx4 v[176:179], v[96:97], off offset:3072
	v_mul_f32_e32 v180, v29, v29
	v_mul_f32_e32 v182, v31, v31
	v_fmac_f32_e32 v180, v28, v28
	v_fmac_f32_e32 v182, v30, v30
	v_add_f32_e32 v180, v180, v182
	v_mul_f32_e32 v181, v25, v25
	v_mul_f32_e32 v182, v27, v27
	v_fmac_f32_e32 v181, v24, v24
	v_fmac_f32_e32 v182, v26, v26
	v_add_f32_e32 v181, v181, v182
	v_add_f32_e32 v180, v180, v181
	v_mul_f32_e32 v181, v21, v21
	v_mul_f32_e32 v182, v23, v23
	v_fmac_f32_e32 v181, v20, v20
	v_fmac_f32_e32 v182, v22, v22
	v_add_f32_e32 v181, v181, v182
	v_add_f32_e32 v180, v180, v181
	v_mul_f32_e32 v181, v17, v17
	v_mul_f32_e32 v182, v19, v19
	v_fmac_f32_e32 v181, v16, v16
	v_fmac_f32_e32 v182, v18, v18
	v_add_f32_e32 v181, v181, v182
	v_add_f32_e32 v180, v180, v181
	ds_swizzle_b32 v181, v180 offset:swizzle(SWAP,1)
	s_waitcnt lgkmcnt(0)
	v_add_f32_e32 v180, v180, v181
	ds_swizzle_b32 v181, v180 offset:swizzle(SWAP,2)
	s_waitcnt lgkmcnt(0)
	v_add_f32_e32 v180, v180, v181
	ds_swizzle_b32 v181, v180 offset:swizzle(SWAP,4)
	s_waitcnt lgkmcnt(0)
	v_add_f32_e32 v180, v180, v181
	ds_swizzle_b32 v181, v180 offset:swizzle(SWAP,8)
	s_waitcnt lgkmcnt(0)
	v_add_f32_e32 v180, v180, v181
	ds_swizzle_b32 v181, v180 offset:swizzle(SWAP,16)
	s_waitcnt lgkmcnt(0)
	v_add_f32_e32 v180, v180, v181
	v_mov_b32_e32 v181, v180
	s_nop 1
	v_permlane32_swap_b32_e32 v180, v181
	v_add_f32_e32 v180, v180, v181
	v_fmamk_f32 v180, v180, 0x3a800000, v245
	s_mov_b32 s4, 0xf800000
	v_cmp_gt_f32_e32 vcc, s4, v180
	v_mul_f32_e32 v181, 0x4f800000, v180
	s_nop 0
	v_cndmask_b32_e32 v180, v180, v181, vcc
	v_sqrt_f32_e32 v181, v180
	s_nop 0
	v_add_u32_e32 v182, -1, v181
	v_fma_f32 v186, -v182, v181, v180
	v_cmp_ge_f32_e64 s[4:5], 0, v186
	v_add_u32_e32 v186, 1, v181
	s_nop 0
	v_cndmask_b32_e64 v182, v181, v182, s[4:5]
	v_fma_f32 v181, -v186, v181, v180
	v_cmp_lt_f32_e64 s[4:5], 0, v181
	s_nop 1
	v_cndmask_b32_e64 v181, v182, v186, s[4:5]
	v_mul_f32_e32 v182, 0x37800000, v181
	v_cndmask_b32_e32 v181, v181, v182, vcc
	v_cmp_class_f32_e32 vcc, v180, v250
	s_nop 1
	v_cndmask_b32_e32 v180, v181, v180, vcc
	v_div_scale_f32 v181, s[4:5], v180, v180, 1.0
	v_rcp_f32_e32 v182, v181
	s_nop 0
	v_fma_f32 v186, -v181, v182, 1.0
	v_fmac_f32_e32 v182, v186, v182
	v_div_scale_f32 v186, vcc, 1.0, v180, 1.0
	v_mul_f32_e32 v188, v186, v182
	v_fma_f32 v189, -v181, v188, v186
	v_fmac_f32_e32 v188, v189, v182
	v_fma_f32 v181, -v181, v188, v186
	v_div_fmas_f32 v181, v181, v182, v188
	v_div_fixup_f32 v186, v181, v180, 1.0
	s_waitcnt vmcnt(0)
	v_pk_mul_f32 v[30:31], v[30:31], v[186:187] op_sel_hi:[1,0]
	v_pk_mul_f32 v[28:29], v[28:29], v[186:187] op_sel_hi:[1,0]
	v_pk_mul_f32 v[30:31], v[102:103], v[30:31]
	v_pk_mul_f32 v[28:29], v[100:101], v[28:29]
	v_pk_add_f32 v[116:117], v[116:117], 1.0 op_sel_hi:[1,0]
	v_pk_add_f32 v[118:119], v[118:119], 1.0 op_sel_hi:[1,0]
	v_pk_fma_f32 v[28:29], v[116:117], v[28:29], v[132:133]
	v_pk_fma_f32 v[30:31], v[118:119], v[30:31], v[134:135]
	v_cvt_pk_bf16_f32 v28, v28, v29
	v_cvt_pk_bf16_f32 v29, v30, v31
	global_store_dwordx2 v[50:51], v[28:29], off
	v_pk_mul_f32 v[26:27], v[26:27], v[186:187] op_sel_hi:[1,0]
	v_pk_mul_f32 v[24:25], v[24:25], v[186:187] op_sel_hi:[1,0]
	v_pk_mul_f32 v[26:27], v[106:107], v[26:27]
	v_pk_mul_f32 v[24:25], v[104:105], v[24:25]
	v_pk_add_f32 v[120:121], v[120:121], 1.0 op_sel_hi:[1,0]
	v_pk_add_f32 v[122:123], v[122:123], 1.0 op_sel_hi:[1,0]
	v_pk_fma_f32 v[24:25], v[120:121], v[24:25], v[136:137]
	v_pk_fma_f32 v[26:27], v[122:123], v[26:27], v[138:139]
	v_cvt_pk_bf16_f32 v24, v24, v25
	v_cvt_pk_bf16_f32 v25, v26, v27
	global_store_dwordx2 v[50:51], v[24:25], off offset:512
	v_pk_mul_f32 v[22:23], v[22:23], v[186:187] op_sel_hi:[1,0]
	v_pk_mul_f32 v[20:21], v[20:21], v[186:187] op_sel_hi:[1,0]
	v_pk_mul_f32 v[22:23], v[110:111], v[22:23]
	v_pk_mul_f32 v[20:21], v[108:109], v[20:21]
	v_pk_add_f32 v[124:125], v[124:125], 1.0 op_sel_hi:[1,0]
	v_pk_add_f32 v[126:127], v[126:127], 1.0 op_sel_hi:[1,0]
	v_pk_fma_f32 v[20:21], v[124:125], v[20:21], v[140:141]
	v_pk_fma_f32 v[22:23], v[126:127], v[22:23], v[142:143]
	v_cvt_pk_bf16_f32 v20, v20, v21
	v_cvt_pk_bf16_f32 v21, v22, v23
	global_store_dwordx2 v[50:51], v[20:21], off offset:1024
	v_pk_mul_f32 v[18:19], v[18:19], v[186:187] op_sel_hi:[1,0]
	v_pk_mul_f32 v[16:17], v[16:17], v[186:187] op_sel_hi:[1,0]
	v_pk_mul_f32 v[18:19], v[114:115], v[18:19]
	v_pk_mul_f32 v[16:17], v[112:113], v[16:17]
	v_pk_add_f32 v[128:129], v[128:129], 1.0 op_sel_hi:[1,0]
	v_pk_add_f32 v[130:131], v[130:131], 1.0 op_sel_hi:[1,0]
	v_pk_fma_f32 v[16:17], v[128:129], v[16:17], v[144:145]
	v_pk_fma_f32 v[18:19], v[130:131], v[18:19], v[146:147]
	v_cvt_pk_bf16_f32 v16, v16, v17
	v_cvt_pk_bf16_f32 v17, v18, v19
	global_store_dwordx2 v[50:51], v[16:17], off offset:1536
	s_and_saveexec_b64 s[4:5], s[2:3]
	s_cbranch_execz .LBB0_431
	v_mul_f32_e32 v180, v1, v1
	v_mul_f32_e32 v182, v3, v3
	v_fmac_f32_e32 v180, v0, v0
	v_fmac_f32_e32 v182, v2, v2
	v_add_f32_e32 v180, v180, v182
	v_mul_f32_e32 v181, v5, v5
	v_mul_f32_e32 v182, v7, v7
	v_fmac_f32_e32 v181, v4, v4
	v_fmac_f32_e32 v182, v6, v6
	v_add_f32_e32 v181, v181, v182
	v_add_f32_e32 v180, v180, v181
	v_mul_f32_e32 v181, v9, v9
	v_mul_f32_e32 v182, v11, v11
	v_fmac_f32_e32 v181, v8, v8
	v_fmac_f32_e32 v182, v10, v10
	v_add_f32_e32 v181, v181, v182
	v_add_f32_e32 v180, v180, v181
	v_mul_f32_e32 v181, v13, v13
	v_mul_f32_e32 v182, v15, v15
	v_fmac_f32_e32 v181, v12, v12
	v_fmac_f32_e32 v182, v14, v14
	v_add_f32_e32 v181, v181, v182
	v_add_f32_e32 v180, v180, v181
	ds_swizzle_b32 v181, v180 offset:swizzle(SWAP,1)
	s_waitcnt lgkmcnt(0)
	v_add_f32_e32 v180, v180, v181
	ds_swizzle_b32 v181, v180 offset:swizzle(SWAP,2)
	s_waitcnt lgkmcnt(0)
	v_add_f32_e32 v180, v180, v181
	ds_swizzle_b32 v181, v180 offset:swizzle(SWAP,4)
	s_waitcnt lgkmcnt(0)
	v_add_f32_e32 v180, v180, v181
	ds_swizzle_b32 v181, v180 offset:swizzle(SWAP,8)
	s_waitcnt lgkmcnt(0)
	v_add_f32_e32 v180, v180, v181
	ds_swizzle_b32 v181, v180 offset:swizzle(SWAP,16)
	s_waitcnt lgkmcnt(0)
	v_add_f32_e32 v180, v180, v181
	v_mov_b32_e32 v181, v180
	s_nop 1
	v_permlane32_swap_b32_e32 v180, v181
	v_add_f32_e32 v180, v180, v181
	v_fmamk_f32 v180, v180, 0x3a800000, v245
	s_mov_b32 s2, 0xf800000
	v_cmp_gt_f32_e32 vcc, s2, v180
	v_mul_f32_e32 v181, 0x4f800000, v180
	s_nop 0
	v_cndmask_b32_e32 v180, v180, v181, vcc
	v_sqrt_f32_e32 v181, v180
	s_nop 0
	v_add_u32_e32 v182, -1, v181
	v_fma_f32 v186, -v182, v181, v180
	v_cmp_ge_f32_e64 s[2:3], 0, v186
	v_add_u32_e32 v186, 1, v181
	s_nop 0
	v_cndmask_b32_e64 v182, v181, v182, s[2:3]
	v_fma_f32 v181, -v186, v181, v180
	v_cmp_lt_f32_e64 s[2:3], 0, v181
	s_nop 1
	v_cndmask_b32_e64 v181, v182, v186, s[2:3]
	v_mul_f32_e32 v182, 0x37800000, v181
	v_cndmask_b32_e32 v181, v181, v182, vcc
	v_cmp_class_f32_e32 vcc, v180, v250
	s_nop 1
	v_cndmask_b32_e32 v180, v181, v180, vcc
	v_div_scale_f32 v181, s[2:3], v180, v180, 1.0
	v_rcp_f32_e32 v182, v181
	s_nop 0
	v_fma_f32 v186, -v181, v182, 1.0
	v_fmac_f32_e32 v182, v186, v182
	v_div_scale_f32 v186, vcc, 1.0, v180, 1.0
	v_mul_f32_e32 v188, v186, v182
	v_fma_f32 v189, -v181, v188, v186
	v_fmac_f32_e32 v188, v189, v182
	v_fma_f32 v181, -v181, v188, v186
	v_div_fmas_f32 v181, v181, v182, v188
	v_div_fixup_f32 v186, v181, v180, 1.0
	v_lshlrev_b64 v[62:63], 11, v[62:63]
	v_lshl_add_u64 v[62:63], v[48:49], 0, v[62:63]
	v_pk_mul_f32 v[2:3], v[2:3], v[186:187] op_sel_hi:[1,0]
	v_pk_mul_f32 v[0:1], v[0:1], v[186:187] op_sel_hi:[1,0]
	v_pk_mul_f32 v[2:3], v[102:103], v[2:3]
	v_pk_mul_f32 v[0:1], v[100:101], v[0:1]
	v_pk_add_f32 v[148:149], v[148:149], 1.0 op_sel_hi:[1,0]
	v_pk_add_f32 v[150:151], v[150:151], 1.0 op_sel_hi:[1,0]
	v_pk_fma_f32 v[0:1], v[148:149], v[0:1], v[164:165]
	v_pk_fma_f32 v[2:3], v[150:151], v[2:3], v[166:167]
	v_cvt_pk_bf16_f32 v0, v0, v1
	v_cvt_pk_bf16_f32 v1, v2, v3
	global_store_dwordx2 v[62:63], v[0:1], off
	v_pk_mul_f32 v[6:7], v[6:7], v[186:187] op_sel_hi:[1,0]
	v_pk_mul_f32 v[4:5], v[4:5], v[186:187] op_sel_hi:[1,0]
	v_pk_mul_f32 v[6:7], v[106:107], v[6:7]
	v_pk_mul_f32 v[4:5], v[104:105], v[4:5]
	v_pk_add_f32 v[152:153], v[152:153], 1.0 op_sel_hi:[1,0]
	v_pk_add_f32 v[154:155], v[154:155], 1.0 op_sel_hi:[1,0]
	v_pk_fma_f32 v[4:5], v[152:153], v[4:5], v[168:169]
	v_pk_fma_f32 v[6:7], v[154:155], v[6:7], v[170:171]
	v_cvt_pk_bf16_f32 v4, v4, v5
	v_cvt_pk_bf16_f32 v5, v6, v7
	global_store_dwordx2 v[62:63], v[4:5], off offset:512
	v_pk_mul_f32 v[10:11], v[10:11], v[186:187] op_sel_hi:[1,0]
	v_pk_mul_f32 v[8:9], v[8:9], v[186:187] op_sel_hi:[1,0]
	v_pk_mul_f32 v[10:11], v[110:111], v[10:11]
	v_pk_mul_f32 v[8:9], v[108:109], v[8:9]
	v_pk_add_f32 v[156:157], v[156:157], 1.0 op_sel_hi:[1,0]
	v_pk_add_f32 v[158:159], v[158:159], 1.0 op_sel_hi:[1,0]
	v_pk_fma_f32 v[8:9], v[156:157], v[8:9], v[172:173]
	v_pk_fma_f32 v[10:11], v[158:159], v[10:11], v[174:175]
	v_cvt_pk_bf16_f32 v8, v8, v9
	v_cvt_pk_bf16_f32 v9, v10, v11
	global_store_dwordx2 v[62:63], v[8:9], off offset:1024
	v_pk_mul_f32 v[14:15], v[14:15], v[186:187] op_sel_hi:[1,0]
	v_pk_mul_f32 v[12:13], v[12:13], v[186:187] op_sel_hi:[1,0]
	v_pk_mul_f32 v[14:15], v[114:115], v[14:15]
	v_pk_mul_f32 v[12:13], v[112:113], v[12:13]
	v_pk_add_f32 v[160:161], v[160:161], 1.0 op_sel_hi:[1,0]
	v_pk_add_f32 v[162:163], v[162:163], 1.0 op_sel_hi:[1,0]
	v_pk_fma_f32 v[12:13], v[160:161], v[12:13], v[176:177]
	v_pk_fma_f32 v[14:15], v[162:163], v[14:15], v[178:179]
	v_cvt_pk_bf16_f32 v12, v12, v13
	v_cvt_pk_bf16_f32 v13, v14, v15
	global_store_dwordx2 v[62:63], v[12:13], off offset:1536
	s_branch .LBB0_431

.LBB0_1237:
	s_mov_b32 s0, 0x8000
	v_add_u32_e32 v152, 0xffff8000, v35
	v_lshl_add_u64 v[150:151], v[32:33], 0, s[10:11]
	v_cmp_gt_i32_e32 vcc, s0, v35
	v_mov_b32_e32 v153, s39
	v_mov_b32_e32 v154, s38
	v_cndmask_b32_e32 v150, v152, v150, vcc
	v_mov_b32_e32 v152, s13
	v_cndmask_b32_e32 v151, 0, v151, vcc
	v_cndmask_b32_e32 v153, v152, v153, vcc
	v_mov_b32_e32 v152, s12
	v_cndmask_b32_e32 v152, v152, v154, vcc
	v_lshlrev_b64 v[150:151], 12, v[150:151]
	v_lshl_add_u64 v[150:151], v[152:153], 0, v[150:151]
	v_lshlrev_b32_e32 v184, 2, v34
	v_lshl_add_u64 v[150:151], v[150:151], 0, v[184:185]
	global_load_dwordx4 v[28:31], v[150:151], off nt
	global_load_dwordx4 v[24:27], v[150:151], off offset:1024 nt
	global_load_dwordx4 v[20:23], v[150:151], off offset:2048 nt
	global_load_dwordx4 v[16:19], v[150:151], off offset:3072 nt
	v_add_u32_e32 v53, s62, v35
	v_cmp_gt_i32_e64 s[0:1], s19, v53
	v_min_i32_e32 v47, 0x8000, v35
	v_ashrrev_i32_e32 v47, 11, v47
	v_mul_hi_i32_i24_e32 v57, 0x6000, v47
	v_mul_i32_i24_e32 v56, 0x6000, v47
	v_lshl_add_u64 v[56:57], s[6:7], 0, v[56:57]
	s_mov_b64 s[2:3], 0x4000
	v_lshl_add_u64 v[54:55], v[56:57], 0, s[2:3]
	s_mov_b64 s[2:3], 0x3000
	v_lshl_add_u64 v[56:57], v[56:57], 0, s[2:3]
	v_lshl_add_u64 v[54:55], v[54:55], 0, v[184:185]
	v_lshl_add_u64 v[56:57], v[56:57], 0, v[184:185]
	global_load_dwordx4 v[70:73], v[36:37], off
	global_load_dwordx4 v[74:77], v[36:37], off offset:1024
	global_load_dwordx4 v[78:81], v[36:37], off offset:2048
	global_load_dwordx4 v[82:85], v[36:37], off offset:3072
	global_load_dwordx4 v[86:89], v[54:55], off
	global_load_dwordx4 v[90:93], v[54:55], off offset:1024
	global_load_dwordx4 v[94:97], v[54:55], off offset:2048
	global_load_dwordx4 v[98:101], v[54:55], off offset:3072
	global_load_dwordx4 v[102:105], v[56:57], off
	global_load_dwordx4 v[106:109], v[56:57], off offset:1024
	global_load_dwordx4 v[110:113], v[56:57], off offset:2048
	global_load_dwordx4 v[114:117], v[56:57], off offset:3072
	s_and_saveexec_b64 s[2:3], s[0:1]
	s_cbranch_execz .Lnm6_skip1
	s_mov_b32 s14, 0x8000
	v_add_u32_e32 v158, 0xffff8000, v53
	v_lshl_add_u64 v[156:157], v[40:41], 0, s[10:11]
	v_cmp_gt_i32_e32 vcc, s14, v53
	v_mov_b32_e32 v159, s39
	v_mov_b32_e32 v160, s38
	v_cndmask_b32_e32 v156, v158, v156, vcc
	v_mov_b32_e32 v158, s13
	v_cndmask_b32_e32 v157, 0, v157, vcc
	v_cndmask_b32_e32 v159, v158, v159, vcc
	v_mov_b32_e32 v158, s12
	v_cndmask_b32_e32 v158, v158, v160, vcc
	v_lshlrev_b64 v[156:157], 12, v[156:157]
	v_lshl_add_u64 v[156:157], v[158:159], 0, v[156:157]
	v_lshl_add_u64 v[156:157], v[156:157], 0, v[184:185]
	global_load_dwordx4 v[12:15], v[156:157], off nt
	global_load_dwordx4 v[8:11], v[156:157], off offset:1024 nt
	global_load_dwordx4 v[4:7], v[156:157], off offset:2048 nt
	global_load_dwordx4 v[0:3], v[156:157], off offset:3072 nt
	v_min_i32_e32 v47, 0x8000, v53
	v_ashrrev_i32_e32 v47, 11, v47
	v_mul_hi_i32_i24_e32 v61, 0x6000, v47
	v_mul_i32_i24_e32 v60, 0x6000, v47
	v_lshl_add_u64 v[60:61], s[6:7], 0, v[60:61]
	s_mov_b64 s[14:15], 0x4000
	v_lshl_add_u64 v[58:59], v[60:61], 0, s[14:15]
	s_mov_b64 s[14:15], 0x3000
	v_lshl_add_u64 v[60:61], v[60:61], 0, s[14:15]
	v_lshl_add_u64 v[58:59], v[58:59], 0, v[184:185]
	v_lshl_add_u64 v[60:61], v[60:61], 0, v[184:185]
	global_load_dwordx4 v[118:121], v[58:59], off
	global_load_dwordx4 v[122:125], v[58:59], off offset:1024
	global_load_dwordx4 v[126:129], v[58:59], off offset:2048
	global_load_dwordx4 v[130:133], v[58:59], off offset:3072
	global_load_dwordx4 v[134:137], v[60:61], off
	global_load_dwordx4 v[138:141], v[60:61], off offset:1024
	global_load_dwordx4 v[142:145], v[60:61], off offset:2048
	global_load_dwordx4 v[146:149], v[60:61], off offset:3072
.Lnm6_skip1:
	s_or_b64 exec, exec, s[2:3]
	v_lshl_add_u64 v[62:63], v[44:45], 0, v[38:39]
	v_add_co_u32_e32 v62, vcc, s17, v62
	s_nop 1
	v_addc_co_u32_e32 v63, vcc, 0, v63, vcc
	v_lshl_add_u64 v[64:65], v[42:43], 0, v[38:39]
	v_add_co_u32_e32 v64, vcc, s17, v64
	s_nop 1
	v_addc_co_u32_e32 v65, vcc, 0, v65, vcc
	s_waitcnt vmcnt(0)
	v_mul_f32_e32 v47, v29, v29
	v_mul_f32_e32 v51, v31, v31
	v_fmac_f32_e32 v47, v28, v28
	v_fmac_f32_e32 v51, v30, v30
	v_add_f32_e32 v47, v47, v51
	v_mul_f32_e32 v49, v25, v25
	v_mul_f32_e32 v51, v27, v27
	v_fmac_f32_e32 v49, v24, v24
	v_fmac_f32_e32 v51, v26, v26
	v_add_f32_e32 v49, v49, v51
	v_add_f32_e32 v47, v47, v49
	v_mul_f32_e32 v49, v21, v21
	v_mul_f32_e32 v51, v23, v23
	v_fmac_f32_e32 v49, v20, v20
	v_fmac_f32_e32 v51, v22, v22
	v_add_f32_e32 v49, v49, v51
	v_add_f32_e32 v47, v47, v49
	v_mul_f32_e32 v49, v17, v17
	v_mul_f32_e32 v51, v19, v19
	v_fmac_f32_e32 v49, v16, v16
	v_fmac_f32_e32 v51, v18, v18
	v_add_f32_e32 v49, v49, v51
	v_add_f32_e32 v47, v47, v49
	ds_swizzle_b32 v49, v47 offset:swizzle(SWAP,1)
	s_waitcnt lgkmcnt(0)
	v_add_f32_e32 v47, v47, v49
	ds_swizzle_b32 v49, v47 offset:swizzle(SWAP,2)
	s_waitcnt lgkmcnt(0)
	v_add_f32_e32 v47, v47, v49
	ds_swizzle_b32 v49, v47 offset:swizzle(SWAP,4)
	s_waitcnt lgkmcnt(0)
	v_add_f32_e32 v47, v47, v49
	ds_swizzle_b32 v49, v47 offset:swizzle(SWAP,8)
	s_waitcnt lgkmcnt(0)
	v_add_f32_e32 v47, v47, v49
	ds_swizzle_b32 v49, v47 offset:swizzle(SWAP,16)
	s_waitcnt lgkmcnt(0)
	v_add_f32_e32 v47, v47, v49
	v_mov_b32_e32 v49, v47
	s_nop 1
	v_permlane32_swap_b32_e32 v47, v49
	v_add_f32_e32 v47, v47, v49
	v_fmamk_f32 v47, v47, 0x3a800000, v245
	s_mov_b32 s2, 0xf800000
	v_cmp_gt_f32_e32 vcc, s2, v47
	v_mul_f32_e32 v49, 0x4f800000, v47
	s_nop 0
	v_cndmask_b32_e32 v47, v47, v49, vcc
	v_sqrt_f32_e32 v49, v47
	s_nop 0
	v_add_u32_e32 v51, -1, v49
	v_fma_f32 v52, -v51, v49, v47
	v_cmp_ge_f32_e64 s[2:3], 0, v52
	v_add_u32_e32 v52, 1, v49
	s_nop 0
	v_cndmask_b32_e64 v51, v49, v51, s[2:3]
	v_fma_f32 v49, -v52, v49, v47
	v_cmp_lt_f32_e64 s[2:3], 0, v49
	s_nop 1
	v_cndmask_b32_e64 v49, v51, v52, s[2:3]
	v_mul_f32_e32 v51, 0x37800000, v49
	v_cndmask_b32_e32 v49, v49, v51, vcc
	v_cmp_class_f32_e32 vcc, v47, v250
	s_nop 1
	v_cndmask_b32_e32 v47, v49, v47, vcc
	v_div_scale_f32 v49, s[2:3], v47, v47, 1.0
	v_rcp_f32_e32 v51, v49
	s_nop 0
	v_fma_f32 v52, -v49, v51, 1.0
	v_fmac_f32_e32 v51, v52, v51
	v_div_scale_f32 v52, vcc, 1.0, v47, 1.0
	v_mul_f32_e32 v66, v52, v51
	v_fma_f32 v67, -v49, v66, v52
	v_fmac_f32_e32 v66, v67, v51
	v_fma_f32 v49, -v49, v66, v52
	v_div_fmas_f32 v49, v49, v51, v66
	v_div_fixup_f32 v52, v49, v47, 1.0
	v_pk_mul_f32 v[30:31], v[30:31], v[52:53] op_sel_hi:[1,0]
	v_pk_mul_f32 v[28:29], v[28:29], v[52:53] op_sel_hi:[1,0]
	v_pk_mul_f32 v[30:31], v[72:73], v[30:31]
	v_pk_mul_f32 v[28:29], v[70:71], v[28:29]
	v_pk_add_f32 v[86:87], v[86:87], 1.0 op_sel_hi:[1,0]
	v_pk_add_f32 v[88:89], v[88:89], 1.0 op_sel_hi:[1,0]
	v_pk_fma_f32 v[28:29], v[86:87], v[28:29], v[102:103]
	v_pk_fma_f32 v[30:31], v[88:89], v[30:31], v[104:105]
	v_cvt_pk_bf16_f32 v28, v28, v29
	v_cvt_pk_bf16_f32 v29, v30, v31
	global_store_dwordx2 v[62:63], v[28:29], off
	v_pk_mul_f32 v[26:27], v[26:27], v[52:53] op_sel_hi:[1,0]
	v_pk_mul_f32 v[24:25], v[24:25], v[52:53] op_sel_hi:[1,0]
	v_pk_mul_f32 v[26:27], v[76:77], v[26:27]
	v_pk_mul_f32 v[24:25], v[74:75], v[24:25]
	v_pk_add_f32 v[90:91], v[90:91], 1.0 op_sel_hi:[1,0]
	v_pk_add_f32 v[92:93], v[92:93], 1.0 op_sel_hi:[1,0]
	v_pk_fma_f32 v[24:25], v[90:91], v[24:25], v[106:107]
	v_pk_fma_f32 v[26:27], v[92:93], v[26:27], v[108:109]
	v_cvt_pk_bf16_f32 v24, v24, v25
	v_cvt_pk_bf16_f32 v25, v26, v27
	global_store_dwordx2 v[62:63], v[24:25], off offset:512
	v_pk_mul_f32 v[22:23], v[22:23], v[52:53] op_sel_hi:[1,0]
	v_pk_mul_f32 v[20:21], v[20:21], v[52:53] op_sel_hi:[1,0]
	v_pk_mul_f32 v[22:23], v[80:81], v[22:23]
	v_pk_mul_f32 v[20:21], v[78:79], v[20:21]
	v_pk_add_f32 v[94:95], v[94:95], 1.0 op_sel_hi:[1,0]
	v_pk_add_f32 v[96:97], v[96:97], 1.0 op_sel_hi:[1,0]
	v_pk_fma_f32 v[20:21], v[94:95], v[20:21], v[110:111]
	v_pk_fma_f32 v[22:23], v[96:97], v[22:23], v[112:113]
	v_cvt_pk_bf16_f32 v20, v20, v21
	v_cvt_pk_bf16_f32 v21, v22, v23
	global_store_dwordx2 v[62:63], v[20:21], off offset:1024
	v_pk_mul_f32 v[18:19], v[18:19], v[52:53] op_sel_hi:[1,0]
	v_pk_mul_f32 v[16:17], v[16:17], v[52:53] op_sel_hi:[1,0]
	v_pk_mul_f32 v[18:19], v[84:85], v[18:19]
	v_pk_mul_f32 v[16:17], v[82:83], v[16:17]
	v_pk_add_f32 v[98:99], v[98:99], 1.0 op_sel_hi:[1,0]
	v_pk_add_f32 v[100:101], v[100:101], 1.0 op_sel_hi:[1,0]
	v_pk_fma_f32 v[16:17], v[98:99], v[16:17], v[114:115]
	v_pk_fma_f32 v[18:19], v[100:101], v[18:19], v[116:117]
	v_cvt_pk_bf16_f32 v16, v16, v17
	v_cvt_pk_bf16_f32 v17, v18, v19
	global_store_dwordx2 v[62:63], v[16:17], off offset:1536
	s_and_saveexec_b64 s[2:3], s[0:1]
	s_cbranch_execz .LBB0_1236
	v_mul_f32_e32 v47, v13, v13
	v_mul_f32_e32 v51, v15, v15
	v_fmac_f32_e32 v47, v12, v12
	v_fmac_f32_e32 v51, v14, v14
	v_add_f32_e32 v47, v47, v51
	v_mul_f32_e32 v49, v9, v9
	v_mul_f32_e32 v51, v11, v11
	v_fmac_f32_e32 v49, v8, v8
	v_fmac_f32_e32 v51, v10, v10
	v_add_f32_e32 v49, v49, v51
	v_add_f32_e32 v47, v47, v49
	v_mul_f32_e32 v49, v5, v5
	v_mul_f32_e32 v51, v7, v7
	v_fmac_f32_e32 v49, v4, v4
	v_fmac_f32_e32 v51, v6, v6
	v_add_f32_e32 v49, v49, v51
	v_add_f32_e32 v47, v47, v49
	v_mul_f32_e32 v49, v1, v1
	v_mul_f32_e32 v51, v3, v3
	v_fmac_f32_e32 v49, v0, v0
	v_fmac_f32_e32 v51, v2, v2
	v_add_f32_e32 v49, v49, v51
	v_add_f32_e32 v47, v47, v49
	ds_swizzle_b32 v49, v47 offset:swizzle(SWAP,1)
	s_waitcnt lgkmcnt(0)
	v_add_f32_e32 v47, v47, v49
	ds_swizzle_b32 v49, v47 offset:swizzle(SWAP,2)
	s_waitcnt lgkmcnt(0)
	v_add_f32_e32 v47, v47, v49
	ds_swizzle_b32 v49, v47 offset:swizzle(SWAP,4)
	s_waitcnt lgkmcnt(0)
	v_add_f32_e32 v47, v47, v49
	ds_swizzle_b32 v49, v47 offset:swizzle(SWAP,8)
	s_waitcnt lgkmcnt(0)
	v_add_f32_e32 v47, v47, v49
	ds_swizzle_b32 v49, v47 offset:swizzle(SWAP,16)
	s_waitcnt lgkmcnt(0)
	v_add_f32_e32 v47, v47, v49
	v_mov_b32_e32 v49, v47
	s_nop 1
	v_permlane32_swap_b32_e32 v47, v49
	v_add_f32_e32 v47, v47, v49
	v_fmamk_f32 v47, v47, 0x3a800000, v245
	s_mov_b32 s0, 0xf800000
	v_cmp_gt_f32_e32 vcc, s0, v47
	v_mul_f32_e32 v49, 0x4f800000, v47
	s_nop 0
	v_cndmask_b32_e32 v47, v47, v49, vcc
	v_sqrt_f32_e32 v49, v47
	s_nop 0
	v_add_u32_e32 v51, -1, v49
	v_fma_f32 v52, -v51, v49, v47
	v_cmp_ge_f32_e64 s[0:1], 0, v52
	v_add_u32_e32 v52, 1, v49
	s_nop 0
	v_cndmask_b32_e64 v51, v49, v51, s[0:1]
	v_fma_f32 v49, -v52, v49, v47
	v_cmp_lt_f32_e64 s[0:1], 0, v49
	s_nop 1
	v_cndmask_b32_e64 v49, v51, v52, s[0:1]
	v_mul_f32_e32 v51, 0x37800000, v49
	v_cndmask_b32_e32 v49, v49, v51, vcc
	v_cmp_class_f32_e32 vcc, v47, v250
	s_nop 1
	v_cndmask_b32_e32 v47, v49, v47, vcc
	v_div_scale_f32 v49, s[0:1], v47, v47, 1.0
	v_rcp_f32_e32 v51, v49
	s_nop 0
	v_fma_f32 v52, -v49, v51, 1.0
	v_fmac_f32_e32 v51, v52, v51
	v_div_scale_f32 v52, vcc, 1.0, v47, 1.0
	v_mul_f32_e32 v66, v52, v51
	v_fma_f32 v67, -v49, v66, v52
	v_fmac_f32_e32 v66, v67, v51
	v_fma_f32 v49, -v49, v66, v52
	v_div_fmas_f32 v49, v49, v51, v66
	v_div_fixup_f32 v52, v49, v47, 1.0
	v_pk_mul_f32 v[14:15], v[14:15], v[52:53] op_sel_hi:[1,0]
	v_pk_mul_f32 v[12:13], v[12:13], v[52:53] op_sel_hi:[1,0]
	v_pk_mul_f32 v[14:15], v[72:73], v[14:15]
	v_pk_mul_f32 v[12:13], v[70:71], v[12:13]
	v_pk_add_f32 v[118:119], v[118:119], 1.0 op_sel_hi:[1,0]
	v_pk_add_f32 v[120:121], v[120:121], 1.0 op_sel_hi:[1,0]
	v_pk_fma_f32 v[12:13], v[118:119], v[12:13], v[134:135]
	v_pk_fma_f32 v[14:15], v[120:121], v[14:15], v[136:137]
	v_cvt_pk_bf16_f32 v12, v12, v13
	v_cvt_pk_bf16_f32 v13, v14, v15
	global_store_dwordx2 v[64:65], v[12:13], off
	v_pk_mul_f32 v[10:11], v[10:11], v[52:53] op_sel_hi:[1,0]
	v_pk_mul_f32 v[8:9], v[8:9], v[52:53] op_sel_hi:[1,0]
	v_pk_mul_f32 v[10:11], v[76:77], v[10:11]
	v_pk_mul_f32 v[8:9], v[74:75], v[8:9]
	v_pk_add_f32 v[122:123], v[122:123], 1.0 op_sel_hi:[1,0]
	v_pk_add_f32 v[124:125], v[124:125], 1.0 op_sel_hi:[1,0]
	v_pk_fma_f32 v[8:9], v[122:123], v[8:9], v[138:139]
	v_pk_fma_f32 v[10:11], v[124:125], v[10:11], v[140:141]
	v_cvt_pk_bf16_f32 v8, v8, v9
	v_cvt_pk_bf16_f32 v9, v10, v11
	global_store_dwordx2 v[64:65], v[8:9], off offset:512
	v_pk_mul_f32 v[6:7], v[6:7], v[52:53] op_sel_hi:[1,0]
	v_pk_mul_f32 v[4:5], v[4:5], v[52:53] op_sel_hi:[1,0]
	v_pk_mul_f32 v[6:7], v[80:81], v[6:7]
	v_pk_mul_f32 v[4:5], v[78:79], v[4:5]
	v_pk_add_f32 v[126:127], v[126:127], 1.0 op_sel_hi:[1,0]
	v_pk_add_f32 v[128:129], v[128:129], 1.0 op_sel_hi:[1,0]
	v_pk_fma_f32 v[4:5], v[126:127], v[4:5], v[142:143]
	v_pk_fma_f32 v[6:7], v[128:129], v[6:7], v[144:145]
	v_cvt_pk_bf16_f32 v4, v4, v5
	v_cvt_pk_bf16_f32 v5, v6, v7
	global_store_dwordx2 v[64:65], v[4:5], off offset:1024
	v_pk_mul_f32 v[2:3], v[2:3], v[52:53] op_sel_hi:[1,0]
	v_pk_mul_f32 v[0:1], v[0:1], v[52:53] op_sel_hi:[1,0]
	v_pk_mul_f32 v[2:3], v[84:85], v[2:3]
	v_pk_mul_f32 v[0:1], v[82:83], v[0:1]
	v_pk_add_f32 v[130:131], v[130:131], 1.0 op_sel_hi:[1,0]
	v_pk_add_f32 v[132:133], v[132:133], 1.0 op_sel_hi:[1,0]
	v_pk_fma_f32 v[0:1], v[130:131], v[0:1], v[146:147]
	v_pk_fma_f32 v[2:3], v[132:133], v[2:3], v[148:149]
	v_cvt_pk_bf16_f32 v0, v0, v1
	v_cvt_pk_bf16_f32 v1, v2, v3
	global_store_dwordx2 v[64:65], v[0:1], off offset:1536
	s_branch .LBB0_1236
